# GEMM K-loops: all per-segment s_setprio flips deleted, no static raise
# speedup vs baseline: 1.0028x; 1.0028x over previous
.LBB0_169:
	s_add_u32 s42, s40, 0xfff80080
	s_addc_u32 s43, s41, -1
	s_add_i32 s52, 0, 0x10000
	s_cmp_eq_u32 s51, 28
	s_cselect_b32 s45, s13, s43
	s_cselect_b32 s44, s47, s42
	s_cselect_b32 s43, s11, s50
	s_cselect_b32 s42, s48, s49
	s_add_i32 s54, 0, 0x14000
	v_add_u32_e32 v142, s52, v175
	v_add_u32_e32 v154, s54, v175
	ds_read_b128 v[130:133], v142
	ds_read_b128 v[134:137], v142 offset:1024
	ds_read_b128 v[138:141], v142 offset:2048
	ds_read_b128 v[142:145], v142 offset:3072
	ds_read_b128 v[170:173], v154
	ds_read_b128 v[184:187], v154 offset:1024
	ds_read_b128 v[188:191], v154 offset:2048
	ds_read_b128 v[192:195], v154 offset:3072
	s_add_i32 m0, s14, 0xc000
	ds_read_b128 v[196:199], v183
	ds_read_b128 v[200:203], v183 offset:1024
	ds_read_b128 v[210:213], v183 offset:2048
	ds_read_b128 v[214:217], v183 offset:3072
	ds_read_b128 v[218:221], v183 offset:4096
	ds_read_b128 v[222:225], v183 offset:5120
	ds_read_b128 v[226:229], v183 offset:6144
	ds_read_b128 v[230:233], v183 offset:7168
	global_load_lds_dwordx4 v166, s[40:41]
	s_add_i32 m0, s14, 0xe000
	s_nop 0
	global_load_lds_dwordx4 v168, s[40:41]
	s_waitcnt vmcnt(8)
	s_waitcnt lgkmcnt(0)
	s_barrier
	s_waitcnt lgkmcnt(0)
	v_mfma_f32_16x16x32_bf16 v[126:129], v[130:133], v[196:199], v[126:129]
	v_mfma_f32_16x16x32_bf16 v[122:125], v[138:141], v[196:199], v[122:125]
	v_mfma_f32_16x16x32_bf16 v[118:121], v[130:133], v[210:213], v[118:121]
	v_mfma_f32_16x16x32_bf16 v[110:113], v[138:141], v[210:213], v[110:113]
	v_mfma_f32_16x16x32_bf16 v[102:105], v[130:133], v[218:221], v[102:105]
	v_mfma_f32_16x16x32_bf16 v[94:97], v[138:141], v[218:221], v[94:97]
	v_mfma_f32_16x16x32_bf16 v[86:89], v[130:133], v[226:229], v[86:89]
	v_mfma_f32_16x16x32_bf16 v[78:81], v[138:141], v[226:229], v[78:81]
	v_mfma_f32_16x16x32_bf16 v[126:129], v[134:137], v[200:203], v[126:129]
	v_mfma_f32_16x16x32_bf16 v[122:125], v[142:145], v[200:203], v[122:125]
	v_mfma_f32_16x16x32_bf16 v[118:121], v[134:137], v[214:217], v[118:121]
	v_mfma_f32_16x16x32_bf16 v[110:113], v[142:145], v[214:217], v[110:113]
	v_mfma_f32_16x16x32_bf16 v[102:105], v[134:137], v[222:225], v[102:105]
	v_mfma_f32_16x16x32_bf16 v[94:97], v[142:145], v[222:225], v[94:97]
	v_mfma_f32_16x16x32_bf16 v[86:89], v[134:137], v[230:233], v[86:89]
	v_mfma_f32_16x16x32_bf16 v[78:81], v[142:145], v[230:233], v[78:81]
	v_mfma_f32_16x16x32_bf16 v[114:117], v[170:173], v[196:199], v[114:117]
	v_mfma_f32_16x16x32_bf16 v[106:109], v[188:191], v[196:199], v[106:109]
	v_mfma_f32_16x16x32_bf16 v[98:101], v[170:173], v[210:213], v[98:101]
	v_mfma_f32_16x16x32_bf16 v[90:93], v[188:191], v[210:213], v[90:93]
	v_mfma_f32_16x16x32_bf16 v[82:85], v[170:173], v[218:221], v[82:85]
	v_mfma_f32_16x16x32_bf16 v[74:77], v[188:191], v[218:221], v[74:77]
	v_mfma_f32_16x16x32_bf16 v[70:73], v[170:173], v[226:229], v[70:73]
	v_mfma_f32_16x16x32_bf16 v[66:69], v[188:191], v[226:229], v[66:69]
	v_mfma_f32_16x16x32_bf16 v[114:117], v[184:187], v[200:203], v[114:117]
	v_mfma_f32_16x16x32_bf16 v[106:109], v[192:195], v[200:203], v[106:109]
	v_mfma_f32_16x16x32_bf16 v[98:101], v[184:187], v[214:217], v[98:101]
	v_mfma_f32_16x16x32_bf16 v[90:93], v[192:195], v[214:217], v[90:93]
	v_mfma_f32_16x16x32_bf16 v[82:85], v[184:187], v[222:225], v[82:85]
	v_mfma_f32_16x16x32_bf16 v[74:77], v[192:195], v[222:225], v[74:77]
	v_mfma_f32_16x16x32_bf16 v[70:73], v[184:187], v[230:233], v[70:73]
	v_mfma_f32_16x16x32_bf16 v[66:69], v[192:195], v[230:233], v[66:69]
	s_barrier
	s_add_i32 s52, s52, s5
	v_lshl_add_u64 v[154:155], s[42:43], 0, v[162:163]
	s_mov_b32 m0, s52
	ds_read_b128 v[196:199], v183 offset:16384
	ds_read_b128 v[200:203], v183 offset:17408
	ds_read_b128 v[210:213], v183 offset:18432
	ds_read_b128 v[214:217], v183 offset:19456
	ds_read_b128 v[218:221], v183 offset:20480
	ds_read_b128 v[222:225], v183 offset:21504
	ds_read_b128 v[226:229], v183 offset:22528
	ds_read_b128 v[230:233], v183 offset:23552
	global_load_lds_dwordx4 v[154:155], off
	s_add_i32 m0, s52, 0x2000
	s_add_u32 s52, s42, 0x80000
	v_lshl_add_u64 v[156:157], s[42:43], 0, v[158:159]
	s_addc_u32 s53, s43, 0
	s_add_i32 s54, s54, s5
	global_load_lds_dwordx4 v[156:157], off
	s_mov_b32 m0, s54
	v_lshl_add_u64 v[180:181], s[44:45], 0, v[160:161]
	global_load_lds_dwordx4 v162, s[52:53]
	s_add_i32 m0, s54, 0x2000
	s_nop 0
	global_load_lds_dwordx4 v158, s[52:53]
	v_lshl_add_u64 v[176:177], s[44:45], 0, v[164:165]
	s_mov_b32 m0, s14
	s_nop 0
	global_load_lds_dwordx4 v[176:177], off
	s_mov_b32 m0, s15
	s_nop 0
	global_load_lds_dwordx4 v[180:181], off
	s_waitcnt vmcnt(8)
	s_waitcnt lgkmcnt(0)
	s_barrier
	s_waitcnt lgkmcnt(0)
	v_mfma_f32_16x16x32_bf16 v[62:65], v[130:133], v[196:199], v[62:65]
	v_mfma_f32_16x16x32_bf16 v[58:61], v[138:141], v[196:199], v[58:61]
	v_mfma_f32_16x16x32_bf16 v[54:57], v[130:133], v[210:213], v[54:57]
	v_mfma_f32_16x16x32_bf16 v[46:49], v[138:141], v[210:213], v[46:49]
	v_mfma_f32_16x16x32_bf16 v[38:41], v[130:133], v[218:221], v[38:41]
	v_mfma_f32_16x16x32_bf16 v[30:33], v[138:141], v[218:221], v[30:33]
	v_mfma_f32_16x16x32_bf16 v[22:25], v[130:133], v[226:229], v[22:25]
	v_mfma_f32_16x16x32_bf16 v[14:17], v[138:141], v[226:229], v[14:17]
	v_mfma_f32_16x16x32_bf16 v[62:65], v[134:137], v[200:203], v[62:65]
	v_mfma_f32_16x16x32_bf16 v[58:61], v[142:145], v[200:203], v[58:61]
	v_mfma_f32_16x16x32_bf16 v[54:57], v[134:137], v[214:217], v[54:57]
	v_mfma_f32_16x16x32_bf16 v[46:49], v[142:145], v[214:217], v[46:49]
	v_mfma_f32_16x16x32_bf16 v[38:41], v[134:137], v[222:225], v[38:41]
	v_mfma_f32_16x16x32_bf16 v[30:33], v[142:145], v[222:225], v[30:33]
	v_mfma_f32_16x16x32_bf16 v[22:25], v[134:137], v[230:233], v[22:25]
	v_mfma_f32_16x16x32_bf16 v[14:17], v[142:145], v[230:233], v[14:17]
	v_mfma_f32_16x16x32_bf16 v[50:53], v[170:173], v[196:199], v[50:53]
	v_mfma_f32_16x16x32_bf16 v[42:45], v[188:191], v[196:199], v[42:45]
	v_mfma_f32_16x16x32_bf16 v[34:37], v[170:173], v[210:213], v[34:37]
	v_mfma_f32_16x16x32_bf16 v[26:29], v[188:191], v[210:213], v[26:29]
	v_mfma_f32_16x16x32_bf16 v[18:21], v[170:173], v[218:221], v[18:21]
	v_mfma_f32_16x16x32_bf16 v[10:13], v[188:191], v[218:221], v[10:13]
	v_mfma_f32_16x16x32_bf16 v[6:9], v[170:173], v[226:229], v[6:9]
	v_mfma_f32_16x16x32_bf16 v[2:5], v[188:191], v[226:229], v[2:5]
	v_mfma_f32_16x16x32_bf16 v[50:53], v[184:187], v[200:203], v[50:53]
	v_mfma_f32_16x16x32_bf16 v[42:45], v[192:195], v[200:203], v[42:45]
	v_mfma_f32_16x16x32_bf16 v[34:37], v[184:187], v[214:217], v[34:37]
	v_mfma_f32_16x16x32_bf16 v[26:29], v[192:195], v[214:217], v[26:29]
	v_mfma_f32_16x16x32_bf16 v[18:21], v[184:187], v[222:225], v[18:21]
	v_mfma_f32_16x16x32_bf16 v[10:13], v[192:195], v[222:225], v[10:13]
	v_mfma_f32_16x16x32_bf16 v[6:9], v[184:187], v[230:233], v[6:9]
	v_mfma_f32_16x16x32_bf16 v[2:5], v[192:195], v[230:233], v[2:5]
	s_barrier
	s_add_i32 s52, 0, 0x18000
	s_add_i32 s53, 0, 0x1c000
	v_add_u32_e32 v142, s52, v175
	v_add_u32_e32 v174, s53, v175
	ds_read_b128 v[130:133], v142
	ds_read_b128 v[134:137], v142 offset:1024
	ds_read_b128 v[138:141], v142 offset:2048
	ds_read_b128 v[142:145], v142 offset:3072
	ds_read_b128 v[170:173], v174
	ds_read_b128 v[184:187], v174 offset:1024
	ds_read_b128 v[188:191], v174 offset:2048
	ds_read_b128 v[192:195], v174 offset:3072
	s_add_u32 s44, s44, 0x80000
	s_addc_u32 s45, s45, 0
	s_mov_b32 m0, s16
	ds_read_b128 v[196:199], v183 offset:32768
	ds_read_b128 v[200:203], v183 offset:33792
	ds_read_b128 v[210:213], v183 offset:34816
	ds_read_b128 v[214:217], v183 offset:35840
	ds_read_b128 v[218:221], v183 offset:36864
	ds_read_b128 v[222:225], v183 offset:37888
	ds_read_b128 v[226:229], v183 offset:38912
	ds_read_b128 v[230:233], v183 offset:39936
	global_load_lds_dwordx4 v164, s[44:45]
	s_mov_b32 m0, s18
	s_nop 0
	global_load_lds_dwordx4 v160, s[44:45]
	s_waitcnt vmcnt(8)
	s_waitcnt lgkmcnt(0)
	s_barrier
	s_waitcnt lgkmcnt(0)
	v_mfma_f32_16x16x32_bf16 v[126:129], v[130:133], v[196:199], v[126:129]
	v_mfma_f32_16x16x32_bf16 v[122:125], v[138:141], v[196:199], v[122:125]
	v_mfma_f32_16x16x32_bf16 v[118:121], v[130:133], v[210:213], v[118:121]
	v_mfma_f32_16x16x32_bf16 v[110:113], v[138:141], v[210:213], v[110:113]
	v_mfma_f32_16x16x32_bf16 v[102:105], v[130:133], v[218:221], v[102:105]
	v_mfma_f32_16x16x32_bf16 v[94:97], v[138:141], v[218:221], v[94:97]
	v_mfma_f32_16x16x32_bf16 v[86:89], v[130:133], v[226:229], v[86:89]
	v_mfma_f32_16x16x32_bf16 v[78:81], v[138:141], v[226:229], v[78:81]
	v_mfma_f32_16x16x32_bf16 v[126:129], v[134:137], v[200:203], v[126:129]
	v_mfma_f32_16x16x32_bf16 v[122:125], v[142:145], v[200:203], v[122:125]
	v_mfma_f32_16x16x32_bf16 v[118:121], v[134:137], v[214:217], v[118:121]
	v_mfma_f32_16x16x32_bf16 v[110:113], v[142:145], v[214:217], v[110:113]
	v_mfma_f32_16x16x32_bf16 v[102:105], v[134:137], v[222:225], v[102:105]
	v_mfma_f32_16x16x32_bf16 v[94:97], v[142:145], v[222:225], v[94:97]
	v_mfma_f32_16x16x32_bf16 v[86:89], v[134:137], v[230:233], v[86:89]
	v_mfma_f32_16x16x32_bf16 v[78:81], v[142:145], v[230:233], v[78:81]
	v_mfma_f32_16x16x32_bf16 v[114:117], v[170:173], v[196:199], v[114:117]
	v_mfma_f32_16x16x32_bf16 v[106:109], v[188:191], v[196:199], v[106:109]
	v_mfma_f32_16x16x32_bf16 v[98:101], v[170:173], v[210:213], v[98:101]
	v_mfma_f32_16x16x32_bf16 v[90:93], v[188:191], v[210:213], v[90:93]
	v_mfma_f32_16x16x32_bf16 v[82:85], v[170:173], v[218:221], v[82:85]
	v_mfma_f32_16x16x32_bf16 v[74:77], v[188:191], v[218:221], v[74:77]
	v_mfma_f32_16x16x32_bf16 v[70:73], v[170:173], v[226:229], v[70:73]
	v_mfma_f32_16x16x32_bf16 v[66:69], v[188:191], v[226:229], v[66:69]
	v_mfma_f32_16x16x32_bf16 v[114:117], v[184:187], v[200:203], v[114:117]
	v_mfma_f32_16x16x32_bf16 v[106:109], v[192:195], v[200:203], v[106:109]
	v_mfma_f32_16x16x32_bf16 v[98:101], v[184:187], v[214:217], v[98:101]
	v_mfma_f32_16x16x32_bf16 v[90:93], v[192:195], v[214:217], v[90:93]
	v_mfma_f32_16x16x32_bf16 v[82:85], v[184:187], v[222:225], v[82:85]
	v_mfma_f32_16x16x32_bf16 v[74:77], v[192:195], v[222:225], v[74:77]
	v_mfma_f32_16x16x32_bf16 v[70:73], v[184:187], v[230:233], v[70:73]
	v_mfma_f32_16x16x32_bf16 v[66:69], v[192:195], v[230:233], v[66:69]
	s_barrier
	s_add_i32 s44, s52, s5
	v_lshl_add_u64 v[154:155], v[154:155], 0, s[34:35]
	s_mov_b32 m0, s44
	ds_read_b128 v[196:199], v183 offset:49152
	ds_read_b128 v[200:203], v183 offset:50176
	ds_read_b128 v[210:213], v183 offset:51200
	ds_read_b128 v[214:217], v183 offset:52224
	ds_read_b128 v[218:221], v183 offset:53248
	ds_read_b128 v[222:225], v183 offset:54272
	ds_read_b128 v[226:229], v183 offset:55296
	ds_read_b128 v[230:233], v183 offset:56320
	global_load_lds_dwordx4 v[154:155], off
	s_add_i32 m0, s44, 0x2000
	s_add_u32 s42, s42, 0x80080
	v_lshl_add_u64 v[154:155], v[156:157], 0, s[34:35]
	s_addc_u32 s43, s43, 0
	s_add_i32 s44, s53, s5
	global_load_lds_dwordx4 v[154:155], off
	s_mov_b32 m0, s44
	s_nop 0
	global_load_lds_dwordx4 v162, s[42:43]
	s_add_i32 m0, s44, 0x2000
	s_nop 0
	global_load_lds_dwordx4 v158, s[42:43]
	v_lshl_add_u64 v[154:155], v[176:177], 0, s[34:35]
	s_mov_b32 m0, s19
	s_nop 0
	global_load_lds_dwordx4 v[154:155], off
	v_lshl_add_u64 v[154:155], v[180:181], 0, s[34:35]
	s_mov_b32 m0, s25
	s_nop 0
	global_load_lds_dwordx4 v[154:155], off
	s_waitcnt vmcnt(8)
	s_waitcnt lgkmcnt(0)
	s_barrier
	s_waitcnt lgkmcnt(0)
	v_mfma_f32_16x16x32_bf16 v[62:65], v[130:133], v[196:199], v[62:65]
	v_mfma_f32_16x16x32_bf16 v[58:61], v[138:141], v[196:199], v[58:61]
	v_mfma_f32_16x16x32_bf16 v[54:57], v[130:133], v[210:213], v[54:57]
	v_mfma_f32_16x16x32_bf16 v[46:49], v[138:141], v[210:213], v[46:49]
	v_mfma_f32_16x16x32_bf16 v[38:41], v[130:133], v[218:221], v[38:41]
	v_mfma_f32_16x16x32_bf16 v[30:33], v[138:141], v[218:221], v[30:33]
	v_mfma_f32_16x16x32_bf16 v[22:25], v[130:133], v[226:229], v[22:25]
	v_mfma_f32_16x16x32_bf16 v[14:17], v[138:141], v[226:229], v[14:17]
	v_mfma_f32_16x16x32_bf16 v[62:65], v[134:137], v[200:203], v[62:65]
	v_mfma_f32_16x16x32_bf16 v[58:61], v[142:145], v[200:203], v[58:61]
	v_mfma_f32_16x16x32_bf16 v[54:57], v[134:137], v[214:217], v[54:57]
	v_mfma_f32_16x16x32_bf16 v[46:49], v[142:145], v[214:217], v[46:49]
	v_mfma_f32_16x16x32_bf16 v[38:41], v[134:137], v[222:225], v[38:41]
	v_mfma_f32_16x16x32_bf16 v[30:33], v[142:145], v[222:225], v[30:33]
	v_mfma_f32_16x16x32_bf16 v[22:25], v[134:137], v[230:233], v[22:25]
	v_mfma_f32_16x16x32_bf16 v[14:17], v[142:145], v[230:233], v[14:17]
	v_mfma_f32_16x16x32_bf16 v[50:53], v[170:173], v[196:199], v[50:53]
	v_mfma_f32_16x16x32_bf16 v[42:45], v[188:191], v[196:199], v[42:45]
	v_mfma_f32_16x16x32_bf16 v[34:37], v[170:173], v[210:213], v[34:37]
	v_mfma_f32_16x16x32_bf16 v[26:29], v[188:191], v[210:213], v[26:29]
	v_mfma_f32_16x16x32_bf16 v[18:21], v[170:173], v[218:221], v[18:21]
	v_mfma_f32_16x16x32_bf16 v[10:13], v[188:191], v[218:221], v[10:13]
	v_mfma_f32_16x16x32_bf16 v[6:9], v[170:173], v[226:229], v[6:9]
	v_mfma_f32_16x16x32_bf16 v[2:5], v[188:191], v[226:229], v[2:5]
	v_mfma_f32_16x16x32_bf16 v[50:53], v[184:187], v[200:203], v[50:53]
	v_mfma_f32_16x16x32_bf16 v[42:45], v[192:195], v[200:203], v[42:45]
	v_mfma_f32_16x16x32_bf16 v[34:37], v[184:187], v[214:217], v[34:37]
	v_mfma_f32_16x16x32_bf16 v[26:29], v[192:195], v[214:217], v[26:29]
	v_mfma_f32_16x16x32_bf16 v[18:21], v[184:187], v[222:225], v[18:21]
	v_mfma_f32_16x16x32_bf16 v[10:13], v[192:195], v[222:225], v[10:13]
	v_mfma_f32_16x16x32_bf16 v[6:9], v[184:187], v[230:233], v[6:9]
	v_mfma_f32_16x16x32_bf16 v[2:5], v[192:195], v[230:233], v[2:5]
	s_barrier
	s_add_i32 s51, s51, 2
	s_add_u32 s40, s40, 0x100
	s_addc_u32 s41, s41, 0
	s_add_u32 s49, s49, 0x100
	s_addc_u32 s50, s50, 0
	s_cmp_gt_u32 s51, 29
	s_cbranch_scc0 .LBB0_169
	s_and_b64 vcc, exec, s[8:9]
	s_cbranch_vccz .LBB0_172
	s_barrier

.LBB0_516:
	s_add_u32 s46, s44, 0xfff80080
	s_addc_u32 s47, s45, -1
	s_add_i32 s58, 0, 0x10000
	s_cmp_eq_u32 s57, 28
	s_cselect_b32 s49, s21, s47
	s_cselect_b32 s48, s50, s46
	s_cselect_b32 s47, s13, s56
	s_cselect_b32 s46, s51, s55
	s_add_i32 s60, 0, 0x14000
	v_add_u32_e32 v102, s58, v172
	v_add_u32_e32 v175, s60, v172
	ds_read_b128 v[82:85], v102
	ds_read_b128 v[86:89], v102 offset:1024
	ds_read_b128 v[98:101], v102 offset:2048
	ds_read_b128 v[102:105], v102 offset:3072
	ds_read_b128 v[154:157], v175
	ds_read_b128 v[168:171], v175 offset:1024
	ds_read_b128 v[176:179], v175 offset:2048
	ds_read_b128 v[180:183], v175 offset:3072
	s_add_i32 m0, s14, 0xc000
	ds_read_b128 v[184:187], v174
	ds_read_b128 v[188:191], v174 offset:1024
	ds_read_b128 v[192:195], v174 offset:2048
	ds_read_b128 v[196:199], v174 offset:3072
	ds_read_b128 v[200:203], v174 offset:4096
	ds_read_b128 v[210:213], v174 offset:5120
	ds_read_b128 v[214:217], v174 offset:6144
	ds_read_b128 v[218:221], v174 offset:7168
	global_load_lds_dwordx4 v164, s[44:45]
	s_add_i32 m0, s14, 0xe000
	s_nop 0
	global_load_lds_dwordx4 v166, s[44:45]
	s_waitcnt vmcnt(8)
	s_waitcnt lgkmcnt(0)
	s_barrier
	s_waitcnt lgkmcnt(0)
	v_mfma_f32_16x16x32_bf16 v[142:145], v[82:85], v[184:187], v[142:145]
	v_mfma_f32_16x16x32_bf16 v[138:141], v[98:101], v[184:187], v[138:141]
	v_mfma_f32_16x16x32_bf16 v[126:129], v[82:85], v[192:195], v[126:129]
	v_mfma_f32_16x16x32_bf16 v[122:125], v[98:101], v[192:195], v[122:125]
	v_mfma_f32_16x16x32_bf16 v[110:113], v[82:85], v[200:203], v[110:113]
	v_mfma_f32_16x16x32_bf16 v[106:109], v[98:101], v[200:203], v[106:109]
	v_mfma_f32_16x16x32_bf16 v[78:81], v[82:85], v[214:217], v[78:81]
	v_mfma_f32_16x16x32_bf16 v[74:77], v[98:101], v[214:217], v[74:77]
	v_mfma_f32_16x16x32_bf16 v[142:145], v[86:89], v[188:191], v[142:145]
	v_mfma_f32_16x16x32_bf16 v[138:141], v[102:105], v[188:191], v[138:141]
	v_mfma_f32_16x16x32_bf16 v[126:129], v[86:89], v[196:199], v[126:129]
	v_mfma_f32_16x16x32_bf16 v[122:125], v[102:105], v[196:199], v[122:125]
	v_mfma_f32_16x16x32_bf16 v[110:113], v[86:89], v[210:213], v[110:113]
	v_mfma_f32_16x16x32_bf16 v[106:109], v[102:105], v[210:213], v[106:109]
	v_mfma_f32_16x16x32_bf16 v[78:81], v[86:89], v[218:221], v[78:81]
	v_mfma_f32_16x16x32_bf16 v[74:77], v[102:105], v[218:221], v[74:77]
	v_mfma_f32_16x16x32_bf16 v[134:137], v[154:157], v[184:187], v[134:137]
	v_mfma_f32_16x16x32_bf16 v[130:133], v[176:179], v[184:187], v[130:133]
	v_mfma_f32_16x16x32_bf16 v[118:121], v[154:157], v[192:195], v[118:121]
	v_mfma_f32_16x16x32_bf16 v[114:117], v[176:179], v[192:195], v[114:117]
	v_mfma_f32_16x16x32_bf16 v[94:97], v[154:157], v[200:203], v[94:97]
	v_mfma_f32_16x16x32_bf16 v[90:93], v[176:179], v[200:203], v[90:93]
	v_mfma_f32_16x16x32_bf16 v[70:73], v[154:157], v[214:217], v[70:73]
	v_mfma_f32_16x16x32_bf16 v[66:69], v[176:179], v[214:217], v[66:69]
	v_mfma_f32_16x16x32_bf16 v[134:137], v[168:171], v[188:191], v[134:137]
	v_mfma_f32_16x16x32_bf16 v[130:133], v[180:183], v[188:191], v[130:133]
	v_mfma_f32_16x16x32_bf16 v[118:121], v[168:171], v[196:199], v[118:121]
	v_mfma_f32_16x16x32_bf16 v[114:117], v[180:183], v[196:199], v[114:117]
	v_mfma_f32_16x16x32_bf16 v[94:97], v[168:171], v[210:213], v[94:97]
	v_mfma_f32_16x16x32_bf16 v[90:93], v[180:183], v[210:213], v[90:93]
	v_mfma_f32_16x16x32_bf16 v[70:73], v[168:171], v[218:221], v[70:73]
	v_mfma_f32_16x16x32_bf16 v[66:69], v[180:183], v[218:221], v[66:69]
	s_barrier
	s_add_i32 s58, s58, s5
	v_lshl_add_u64 v[222:223], s[46:47], 0, v[0:1]
	s_mov_b32 m0, s58
	ds_read_b128 v[184:187], v174 offset:16384
	ds_read_b128 v[188:191], v174 offset:17408
	ds_read_b128 v[192:195], v174 offset:18432
	ds_read_b128 v[196:199], v174 offset:19456
	ds_read_b128 v[200:203], v174 offset:20480
	ds_read_b128 v[210:213], v174 offset:21504
	ds_read_b128 v[214:217], v174 offset:22528
	ds_read_b128 v[218:221], v174 offset:23552
	global_load_lds_dwordx4 v[222:223], off
	s_add_i32 m0, s58, 0x2000
	s_add_u32 s58, s46, 0x80000
	v_lshl_add_u64 v[224:225], s[46:47], 0, v[158:159]
	s_addc_u32 s59, s47, 0
	s_add_i32 s60, s60, s5
	global_load_lds_dwordx4 v[224:225], off
	s_mov_b32 m0, s60
	v_lshl_add_u64 v[228:229], s[48:49], 0, v[160:161]
	global_load_lds_dwordx4 v0, s[58:59]
	s_add_i32 m0, s60, 0x2000
	s_nop 0
	global_load_lds_dwordx4 v158, s[58:59]
	v_lshl_add_u64 v[226:227], s[48:49], 0, v[162:163]
	s_mov_b32 m0, s14
	s_nop 0
	global_load_lds_dwordx4 v[226:227], off
	s_mov_b32 m0, s15
	s_nop 0
	global_load_lds_dwordx4 v[228:229], off
	s_waitcnt vmcnt(8)
	s_waitcnt lgkmcnt(0)
	s_barrier
	s_waitcnt lgkmcnt(0)
	v_mfma_f32_16x16x32_bf16 v[62:65], v[82:85], v[184:187], v[62:65]
	v_mfma_f32_16x16x32_bf16 v[58:61], v[98:101], v[184:187], v[58:61]
	v_mfma_f32_16x16x32_bf16 v[46:49], v[82:85], v[192:195], v[46:49]
	v_mfma_f32_16x16x32_bf16 v[42:45], v[98:101], v[192:195], v[42:45]
	v_mfma_f32_16x16x32_bf16 v[30:33], v[82:85], v[200:203], v[30:33]
	v_mfma_f32_16x16x32_bf16 v[26:29], v[98:101], v[200:203], v[26:29]
	v_mfma_f32_16x16x32_bf16 v[14:17], v[82:85], v[214:217], v[14:17]
	v_mfma_f32_16x16x32_bf16 v[10:13], v[98:101], v[214:217], v[10:13]
	v_mfma_f32_16x16x32_bf16 v[62:65], v[86:89], v[188:191], v[62:65]
	v_mfma_f32_16x16x32_bf16 v[58:61], v[102:105], v[188:191], v[58:61]
	v_mfma_f32_16x16x32_bf16 v[46:49], v[86:89], v[196:199], v[46:49]
	v_mfma_f32_16x16x32_bf16 v[42:45], v[102:105], v[196:199], v[42:45]
	v_mfma_f32_16x16x32_bf16 v[30:33], v[86:89], v[210:213], v[30:33]
	v_mfma_f32_16x16x32_bf16 v[26:29], v[102:105], v[210:213], v[26:29]
	v_mfma_f32_16x16x32_bf16 v[14:17], v[86:89], v[218:221], v[14:17]
	v_mfma_f32_16x16x32_bf16 v[10:13], v[102:105], v[218:221], v[10:13]
	v_mfma_f32_16x16x32_bf16 v[54:57], v[154:157], v[184:187], v[54:57]
	v_mfma_f32_16x16x32_bf16 v[50:53], v[176:179], v[184:187], v[50:53]
	v_mfma_f32_16x16x32_bf16 v[38:41], v[154:157], v[192:195], v[38:41]
	v_mfma_f32_16x16x32_bf16 v[34:37], v[176:179], v[192:195], v[34:37]
	v_mfma_f32_16x16x32_bf16 v[22:25], v[154:157], v[200:203], v[22:25]
	v_mfma_f32_16x16x32_bf16 v[18:21], v[176:179], v[200:203], v[18:21]
	v_mfma_f32_16x16x32_bf16 v[6:9], v[154:157], v[214:217], v[6:9]
	v_mfma_f32_16x16x32_bf16 v[2:5], v[176:179], v[214:217], v[2:5]
	v_mfma_f32_16x16x32_bf16 v[54:57], v[168:171], v[188:191], v[54:57]
	v_mfma_f32_16x16x32_bf16 v[50:53], v[180:183], v[188:191], v[50:53]
	v_mfma_f32_16x16x32_bf16 v[38:41], v[168:171], v[196:199], v[38:41]
	v_mfma_f32_16x16x32_bf16 v[34:37], v[180:183], v[196:199], v[34:37]
	v_mfma_f32_16x16x32_bf16 v[22:25], v[168:171], v[210:213], v[22:25]
	v_mfma_f32_16x16x32_bf16 v[18:21], v[180:183], v[210:213], v[18:21]
	v_mfma_f32_16x16x32_bf16 v[6:9], v[168:171], v[218:221], v[6:9]
	v_mfma_f32_16x16x32_bf16 v[2:5], v[180:183], v[218:221], v[2:5]
	s_barrier
	s_add_i32 s58, 0, 0x18000
	s_add_i32 s59, 0, 0x1c000
	v_add_u32_e32 v102, s58, v172
	v_add_u32_e32 v175, s59, v172
	ds_read_b128 v[82:85], v102
	ds_read_b128 v[86:89], v102 offset:1024
	ds_read_b128 v[98:101], v102 offset:2048
	ds_read_b128 v[102:105], v102 offset:3072
	ds_read_b128 v[154:157], v175
	ds_read_b128 v[168:171], v175 offset:1024
	ds_read_b128 v[176:179], v175 offset:2048
	ds_read_b128 v[180:183], v175 offset:3072
	s_add_u32 s48, s48, 0x80000
	s_addc_u32 s49, s49, 0
	s_mov_b32 m0, s16
	ds_read_b128 v[184:187], v174 offset:32768
	ds_read_b128 v[188:191], v174 offset:33792
	ds_read_b128 v[192:195], v174 offset:34816
	ds_read_b128 v[196:199], v174 offset:35840
	ds_read_b128 v[200:203], v174 offset:36864
	ds_read_b128 v[210:213], v174 offset:37888
	ds_read_b128 v[214:217], v174 offset:38912
	ds_read_b128 v[218:221], v174 offset:39936
	global_load_lds_dwordx4 v162, s[48:49]
	s_mov_b32 m0, s18
	s_nop 0
	global_load_lds_dwordx4 v160, s[48:49]
	s_waitcnt vmcnt(8)
	s_waitcnt lgkmcnt(0)
	s_barrier
	s_waitcnt lgkmcnt(0)
	v_mfma_f32_16x16x32_bf16 v[142:145], v[82:85], v[184:187], v[142:145]
	v_mfma_f32_16x16x32_bf16 v[138:141], v[98:101], v[184:187], v[138:141]
	v_mfma_f32_16x16x32_bf16 v[126:129], v[82:85], v[192:195], v[126:129]
	v_mfma_f32_16x16x32_bf16 v[122:125], v[98:101], v[192:195], v[122:125]
	v_mfma_f32_16x16x32_bf16 v[110:113], v[82:85], v[200:203], v[110:113]
	v_mfma_f32_16x16x32_bf16 v[106:109], v[98:101], v[200:203], v[106:109]
	v_mfma_f32_16x16x32_bf16 v[78:81], v[82:85], v[214:217], v[78:81]
	v_mfma_f32_16x16x32_bf16 v[74:77], v[98:101], v[214:217], v[74:77]
	v_mfma_f32_16x16x32_bf16 v[142:145], v[86:89], v[188:191], v[142:145]
	v_mfma_f32_16x16x32_bf16 v[138:141], v[102:105], v[188:191], v[138:141]
	v_mfma_f32_16x16x32_bf16 v[126:129], v[86:89], v[196:199], v[126:129]
	v_mfma_f32_16x16x32_bf16 v[122:125], v[102:105], v[196:199], v[122:125]
	v_mfma_f32_16x16x32_bf16 v[110:113], v[86:89], v[210:213], v[110:113]
	v_mfma_f32_16x16x32_bf16 v[106:109], v[102:105], v[210:213], v[106:109]
	v_mfma_f32_16x16x32_bf16 v[78:81], v[86:89], v[218:221], v[78:81]
	v_mfma_f32_16x16x32_bf16 v[74:77], v[102:105], v[218:221], v[74:77]
	v_mfma_f32_16x16x32_bf16 v[134:137], v[154:157], v[184:187], v[134:137]
	v_mfma_f32_16x16x32_bf16 v[130:133], v[176:179], v[184:187], v[130:133]
	v_mfma_f32_16x16x32_bf16 v[118:121], v[154:157], v[192:195], v[118:121]
	v_mfma_f32_16x16x32_bf16 v[114:117], v[176:179], v[192:195], v[114:117]
	v_mfma_f32_16x16x32_bf16 v[94:97], v[154:157], v[200:203], v[94:97]
	v_mfma_f32_16x16x32_bf16 v[90:93], v[176:179], v[200:203], v[90:93]
	v_mfma_f32_16x16x32_bf16 v[70:73], v[154:157], v[214:217], v[70:73]
	v_mfma_f32_16x16x32_bf16 v[66:69], v[176:179], v[214:217], v[66:69]
	v_mfma_f32_16x16x32_bf16 v[134:137], v[168:171], v[188:191], v[134:137]
	v_mfma_f32_16x16x32_bf16 v[130:133], v[180:183], v[188:191], v[130:133]
	v_mfma_f32_16x16x32_bf16 v[118:121], v[168:171], v[196:199], v[118:121]
	v_mfma_f32_16x16x32_bf16 v[114:117], v[180:183], v[196:199], v[114:117]
	v_mfma_f32_16x16x32_bf16 v[94:97], v[168:171], v[210:213], v[94:97]
	v_mfma_f32_16x16x32_bf16 v[90:93], v[180:183], v[210:213], v[90:93]
	v_mfma_f32_16x16x32_bf16 v[70:73], v[168:171], v[218:221], v[70:73]
	v_mfma_f32_16x16x32_bf16 v[66:69], v[180:183], v[218:221], v[66:69]
	s_barrier
	s_add_i32 s48, s58, s5
	v_lshl_add_u64 v[222:223], v[222:223], 0, s[34:35]
	s_mov_b32 m0, s48
	ds_read_b128 v[184:187], v174 offset:49152
	ds_read_b128 v[188:191], v174 offset:50176
	ds_read_b128 v[192:195], v174 offset:51200
	ds_read_b128 v[196:199], v174 offset:52224
	ds_read_b128 v[200:203], v174 offset:53248
	ds_read_b128 v[210:213], v174 offset:54272
	ds_read_b128 v[214:217], v174 offset:55296
	ds_read_b128 v[218:221], v174 offset:56320
	global_load_lds_dwordx4 v[222:223], off
	s_add_i32 m0, s48, 0x2000
	s_add_u32 s46, s46, 0x80080
	v_lshl_add_u64 v[222:223], v[224:225], 0, s[34:35]
	s_addc_u32 s47, s47, 0
	s_add_i32 s48, s59, s5
	global_load_lds_dwordx4 v[222:223], off
	s_mov_b32 m0, s48
	s_nop 0
	global_load_lds_dwordx4 v0, s[46:47]
	s_add_i32 m0, s48, 0x2000
	s_nop 0
	global_load_lds_dwordx4 v158, s[46:47]
	v_lshl_add_u64 v[222:223], v[226:227], 0, s[34:35]
	s_mov_b32 m0, s25
	s_nop 0
	global_load_lds_dwordx4 v[222:223], off
	v_lshl_add_u64 v[222:223], v[228:229], 0, s[34:35]
	s_mov_b32 m0, s33
	s_nop 0
	global_load_lds_dwordx4 v[222:223], off
	s_waitcnt vmcnt(8)
	s_waitcnt lgkmcnt(0)
	s_barrier
	s_waitcnt lgkmcnt(0)
	v_mfma_f32_16x16x32_bf16 v[62:65], v[82:85], v[184:187], v[62:65]
	v_mfma_f32_16x16x32_bf16 v[58:61], v[98:101], v[184:187], v[58:61]
	v_mfma_f32_16x16x32_bf16 v[46:49], v[82:85], v[192:195], v[46:49]
	v_mfma_f32_16x16x32_bf16 v[42:45], v[98:101], v[192:195], v[42:45]
	v_mfma_f32_16x16x32_bf16 v[30:33], v[82:85], v[200:203], v[30:33]
	v_mfma_f32_16x16x32_bf16 v[26:29], v[98:101], v[200:203], v[26:29]
	v_mfma_f32_16x16x32_bf16 v[14:17], v[82:85], v[214:217], v[14:17]
	v_mfma_f32_16x16x32_bf16 v[10:13], v[98:101], v[214:217], v[10:13]
	v_mfma_f32_16x16x32_bf16 v[62:65], v[86:89], v[188:191], v[62:65]
	v_mfma_f32_16x16x32_bf16 v[58:61], v[102:105], v[188:191], v[58:61]
	v_mfma_f32_16x16x32_bf16 v[46:49], v[86:89], v[196:199], v[46:49]
	v_mfma_f32_16x16x32_bf16 v[42:45], v[102:105], v[196:199], v[42:45]
	v_mfma_f32_16x16x32_bf16 v[30:33], v[86:89], v[210:213], v[30:33]
	v_mfma_f32_16x16x32_bf16 v[26:29], v[102:105], v[210:213], v[26:29]
	v_mfma_f32_16x16x32_bf16 v[14:17], v[86:89], v[218:221], v[14:17]
	v_mfma_f32_16x16x32_bf16 v[10:13], v[102:105], v[218:221], v[10:13]
	v_mfma_f32_16x16x32_bf16 v[54:57], v[154:157], v[184:187], v[54:57]
	v_mfma_f32_16x16x32_bf16 v[50:53], v[176:179], v[184:187], v[50:53]
	v_mfma_f32_16x16x32_bf16 v[38:41], v[154:157], v[192:195], v[38:41]
	v_mfma_f32_16x16x32_bf16 v[34:37], v[176:179], v[192:195], v[34:37]
	v_mfma_f32_16x16x32_bf16 v[22:25], v[154:157], v[200:203], v[22:25]
	v_mfma_f32_16x16x32_bf16 v[18:21], v[176:179], v[200:203], v[18:21]
	v_mfma_f32_16x16x32_bf16 v[6:9], v[154:157], v[214:217], v[6:9]
	v_mfma_f32_16x16x32_bf16 v[2:5], v[176:179], v[214:217], v[2:5]
	v_mfma_f32_16x16x32_bf16 v[54:57], v[168:171], v[188:191], v[54:57]
	v_mfma_f32_16x16x32_bf16 v[50:53], v[180:183], v[188:191], v[50:53]
	v_mfma_f32_16x16x32_bf16 v[38:41], v[168:171], v[196:199], v[38:41]
	v_mfma_f32_16x16x32_bf16 v[34:37], v[180:183], v[196:199], v[34:37]
	v_mfma_f32_16x16x32_bf16 v[22:25], v[168:171], v[210:213], v[22:25]
	v_mfma_f32_16x16x32_bf16 v[18:21], v[180:183], v[210:213], v[18:21]
	v_mfma_f32_16x16x32_bf16 v[6:9], v[168:171], v[218:221], v[6:9]
	v_mfma_f32_16x16x32_bf16 v[2:5], v[180:183], v[218:221], v[2:5]
	s_barrier
	s_add_i32 s57, s57, 2
	s_add_u32 s44, s44, 0x100
	s_addc_u32 s45, s45, 0
	s_add_u32 s55, s55, 0x100
	s_addc_u32 s56, s56, 0
	s_cmp_gt_u32 s57, 29
	s_cbranch_scc0 .LBB0_516
	s_and_b64 vcc, exec, s[10:11]
	s_cbranch_vccz .LBB0_519
	s_barrier

.LBB0_604:
	s_add_u32 s22, s6, 0xfff80080
	s_addc_u32 s23, s7, -1
	s_add_i32 s54, 0, 0x10000
	s_cmp_eq_u32 s53, 28
	s_cselect_b32 s47, s18, s23
	s_cselect_b32 s46, s19, s22
	s_cselect_b32 s23, s21, s52
	s_cselect_b32 s22, s25, s41
	s_add_i32 s56, 0, 0x14000
	v_add_u32_e32 v162, s54, v175
	v_add_u32_e32 v174, s56, v175
	ds_read_b128 v[130:133], v162
	ds_read_b128 v[134:137], v162 offset:1024
	ds_read_b128 v[154:157], v162 offset:2048
	ds_read_b128 v[162:165], v162 offset:3072
	ds_read_b128 v[166:169], v174
	ds_read_b128 v[170:173], v174 offset:1024
	ds_read_b128 v[180:183], v174 offset:2048
	ds_read_b128 v[184:187], v174 offset:3072
	s_add_i32 m0, s16, 0xc000
	ds_read_b128 v[188:191], v179
	ds_read_b128 v[192:195], v179 offset:1024
	ds_read_b128 v[196:199], v179 offset:2048
	ds_read_b128 v[200:203], v179 offset:3072
	ds_read_b128 v[210:213], v179 offset:4096
	ds_read_b128 v[214:217], v179 offset:5120
	ds_read_b128 v[218:221], v179 offset:6144
	ds_read_b128 v[222:225], v179 offset:7168
	global_load_lds_dwordx4 v158, s[6:7]
	s_add_i32 m0, s16, 0xe000
	s_nop 0
	global_load_lds_dwordx4 v160, s[6:7]
	s_waitcnt vmcnt(8)
	s_waitcnt lgkmcnt(0)
	s_barrier
	s_waitcnt lgkmcnt(0)
	v_mfma_f32_16x16x32_bf16 v[126:129], v[130:133], v[188:191], v[126:129]
	v_mfma_f32_16x16x32_bf16 v[122:125], v[154:157], v[188:191], v[122:125]
	v_mfma_f32_16x16x32_bf16 v[110:113], v[130:133], v[196:199], v[110:113]
	v_mfma_f32_16x16x32_bf16 v[106:109], v[154:157], v[196:199], v[106:109]
	v_mfma_f32_16x16x32_bf16 v[94:97], v[130:133], v[210:213], v[94:97]
	v_mfma_f32_16x16x32_bf16 v[90:93], v[154:157], v[210:213], v[90:93]
	v_mfma_f32_16x16x32_bf16 v[78:81], v[130:133], v[218:221], v[78:81]
	v_mfma_f32_16x16x32_bf16 v[74:77], v[154:157], v[218:221], v[74:77]
	v_mfma_f32_16x16x32_bf16 v[126:129], v[134:137], v[192:195], v[126:129]
	v_mfma_f32_16x16x32_bf16 v[122:125], v[162:165], v[192:195], v[122:125]
	v_mfma_f32_16x16x32_bf16 v[110:113], v[134:137], v[200:203], v[110:113]
	v_mfma_f32_16x16x32_bf16 v[106:109], v[162:165], v[200:203], v[106:109]
	v_mfma_f32_16x16x32_bf16 v[94:97], v[134:137], v[214:217], v[94:97]
	v_mfma_f32_16x16x32_bf16 v[90:93], v[162:165], v[214:217], v[90:93]
	v_mfma_f32_16x16x32_bf16 v[78:81], v[134:137], v[222:225], v[78:81]
	v_mfma_f32_16x16x32_bf16 v[74:77], v[162:165], v[222:225], v[74:77]
	v_mfma_f32_16x16x32_bf16 v[118:121], v[166:169], v[188:191], v[118:121]
	v_mfma_f32_16x16x32_bf16 v[114:117], v[180:183], v[188:191], v[114:117]
	v_mfma_f32_16x16x32_bf16 v[102:105], v[166:169], v[196:199], v[102:105]
	v_mfma_f32_16x16x32_bf16 v[98:101], v[180:183], v[196:199], v[98:101]
	v_mfma_f32_16x16x32_bf16 v[86:89], v[166:169], v[210:213], v[86:89]
	v_mfma_f32_16x16x32_bf16 v[82:85], v[180:183], v[210:213], v[82:85]
	v_mfma_f32_16x16x32_bf16 v[70:73], v[166:169], v[218:221], v[70:73]
	v_mfma_f32_16x16x32_bf16 v[66:69], v[180:183], v[218:221], v[66:69]
	v_mfma_f32_16x16x32_bf16 v[118:121], v[170:173], v[192:195], v[118:121]
	v_mfma_f32_16x16x32_bf16 v[114:117], v[184:187], v[192:195], v[114:117]
	v_mfma_f32_16x16x32_bf16 v[102:105], v[170:173], v[200:203], v[102:105]
	v_mfma_f32_16x16x32_bf16 v[98:101], v[184:187], v[200:203], v[98:101]
	v_mfma_f32_16x16x32_bf16 v[86:89], v[170:173], v[214:217], v[86:89]
	v_mfma_f32_16x16x32_bf16 v[82:85], v[184:187], v[214:217], v[82:85]
	v_mfma_f32_16x16x32_bf16 v[70:73], v[170:173], v[222:225], v[70:73]
	v_mfma_f32_16x16x32_bf16 v[66:69], v[184:187], v[222:225], v[66:69]
	s_barrier
	s_add_i32 s54, s54, s15
	v_lshl_add_u64 v[226:227], s[22:23], 0, v[142:143]
	s_mov_b32 m0, s54
	ds_read_b128 v[188:191], v179 offset:16384
	ds_read_b128 v[192:195], v179 offset:17408
	ds_read_b128 v[196:199], v179 offset:18432
	ds_read_b128 v[200:203], v179 offset:19456
	ds_read_b128 v[210:213], v179 offset:20480
	ds_read_b128 v[214:217], v179 offset:21504
	ds_read_b128 v[218:221], v179 offset:22528
	ds_read_b128 v[222:225], v179 offset:23552
	global_load_lds_dwordx4 v[226:227], off
	s_add_i32 m0, s54, 0x2000
	s_add_u32 s54, s22, 0x80000
	v_lshl_add_u64 v[228:229], s[22:23], 0, v[138:139]
	s_addc_u32 s55, s23, 0
	s_add_i32 s56, s56, s15
	global_load_lds_dwordx4 v[228:229], off
	s_mov_b32 m0, s56
	v_lshl_add_u64 v[232:233], s[46:47], 0, v[140:141]
	global_load_lds_dwordx4 v142, s[54:55]
	s_add_i32 m0, s56, 0x2000
	s_nop 0
	global_load_lds_dwordx4 v138, s[54:55]
	v_lshl_add_u64 v[230:231], s[46:47], 0, v[144:145]
	s_mov_b32 m0, s16
	s_nop 0
	global_load_lds_dwordx4 v[230:231], off
	s_mov_b32 m0, s33
	s_nop 0
	global_load_lds_dwordx4 v[232:233], off
	s_waitcnt vmcnt(8)
	s_waitcnt lgkmcnt(0)
	s_barrier
	s_waitcnt lgkmcnt(0)
	v_mfma_f32_16x16x32_bf16 v[62:65], v[130:133], v[188:191], v[62:65]
	v_mfma_f32_16x16x32_bf16 v[58:61], v[154:157], v[188:191], v[58:61]
	v_mfma_f32_16x16x32_bf16 v[46:49], v[130:133], v[196:199], v[46:49]
	v_mfma_f32_16x16x32_bf16 v[42:45], v[154:157], v[196:199], v[42:45]
	v_mfma_f32_16x16x32_bf16 v[30:33], v[130:133], v[210:213], v[30:33]
	v_mfma_f32_16x16x32_bf16 v[26:29], v[154:157], v[210:213], v[26:29]
	v_mfma_f32_16x16x32_bf16 v[14:17], v[130:133], v[218:221], v[14:17]
	v_mfma_f32_16x16x32_bf16 v[10:13], v[154:157], v[218:221], v[10:13]
	v_mfma_f32_16x16x32_bf16 v[62:65], v[134:137], v[192:195], v[62:65]
	v_mfma_f32_16x16x32_bf16 v[58:61], v[162:165], v[192:195], v[58:61]
	v_mfma_f32_16x16x32_bf16 v[46:49], v[134:137], v[200:203], v[46:49]
	v_mfma_f32_16x16x32_bf16 v[42:45], v[162:165], v[200:203], v[42:45]
	v_mfma_f32_16x16x32_bf16 v[30:33], v[134:137], v[214:217], v[30:33]
	v_mfma_f32_16x16x32_bf16 v[26:29], v[162:165], v[214:217], v[26:29]
	v_mfma_f32_16x16x32_bf16 v[14:17], v[134:137], v[222:225], v[14:17]
	v_mfma_f32_16x16x32_bf16 v[10:13], v[162:165], v[222:225], v[10:13]
	v_mfma_f32_16x16x32_bf16 v[54:57], v[166:169], v[188:191], v[54:57]
	v_mfma_f32_16x16x32_bf16 v[50:53], v[180:183], v[188:191], v[50:53]
	v_mfma_f32_16x16x32_bf16 v[38:41], v[166:169], v[196:199], v[38:41]
	v_mfma_f32_16x16x32_bf16 v[34:37], v[180:183], v[196:199], v[34:37]
	v_mfma_f32_16x16x32_bf16 v[22:25], v[166:169], v[210:213], v[22:25]
	v_mfma_f32_16x16x32_bf16 v[18:21], v[180:183], v[210:213], v[18:21]
	v_mfma_f32_16x16x32_bf16 v[6:9], v[166:169], v[218:221], v[6:9]
	v_mfma_f32_16x16x32_bf16 v[2:5], v[180:183], v[218:221], v[2:5]
	v_mfma_f32_16x16x32_bf16 v[54:57], v[170:173], v[192:195], v[54:57]
	v_mfma_f32_16x16x32_bf16 v[50:53], v[184:187], v[192:195], v[50:53]
	v_mfma_f32_16x16x32_bf16 v[38:41], v[170:173], v[200:203], v[38:41]
	v_mfma_f32_16x16x32_bf16 v[34:37], v[184:187], v[200:203], v[34:37]
	v_mfma_f32_16x16x32_bf16 v[22:25], v[170:173], v[214:217], v[22:25]
	v_mfma_f32_16x16x32_bf16 v[18:21], v[184:187], v[214:217], v[18:21]
	v_mfma_f32_16x16x32_bf16 v[6:9], v[170:173], v[222:225], v[6:9]
	v_mfma_f32_16x16x32_bf16 v[2:5], v[184:187], v[222:225], v[2:5]
	s_barrier
	s_add_i32 s54, 0, 0x18000
	s_add_i32 s55, 0, 0x1c000
	v_add_u32_e32 v162, s54, v175
	v_add_u32_e32 v174, s55, v175
	ds_read_b128 v[130:133], v162
	ds_read_b128 v[134:137], v162 offset:1024
	ds_read_b128 v[154:157], v162 offset:2048
	ds_read_b128 v[162:165], v162 offset:3072
	ds_read_b128 v[166:169], v174
	ds_read_b128 v[170:173], v174 offset:1024
	ds_read_b128 v[180:183], v174 offset:2048
	ds_read_b128 v[184:187], v174 offset:3072
	s_add_u32 s46, s46, 0x80000
	s_addc_u32 s47, s47, 0
	s_mov_b32 m0, s37
	ds_read_b128 v[188:191], v179 offset:32768
	ds_read_b128 v[192:195], v179 offset:33792
	ds_read_b128 v[196:199], v179 offset:34816
	ds_read_b128 v[200:203], v179 offset:35840
	ds_read_b128 v[210:213], v179 offset:36864
	ds_read_b128 v[214:217], v179 offset:37888
	ds_read_b128 v[218:221], v179 offset:38912
	ds_read_b128 v[222:225], v179 offset:39936
	global_load_lds_dwordx4 v144, s[46:47]
	s_mov_b32 m0, s48
	s_nop 0
	global_load_lds_dwordx4 v140, s[46:47]
	s_waitcnt vmcnt(8)
	s_waitcnt lgkmcnt(0)
	s_barrier
	s_waitcnt lgkmcnt(0)
	v_mfma_f32_16x16x32_bf16 v[126:129], v[130:133], v[188:191], v[126:129]
	v_mfma_f32_16x16x32_bf16 v[122:125], v[154:157], v[188:191], v[122:125]
	v_mfma_f32_16x16x32_bf16 v[110:113], v[130:133], v[196:199], v[110:113]
	v_mfma_f32_16x16x32_bf16 v[106:109], v[154:157], v[196:199], v[106:109]
	v_mfma_f32_16x16x32_bf16 v[94:97], v[130:133], v[210:213], v[94:97]
	v_mfma_f32_16x16x32_bf16 v[90:93], v[154:157], v[210:213], v[90:93]
	v_mfma_f32_16x16x32_bf16 v[78:81], v[130:133], v[218:221], v[78:81]
	v_mfma_f32_16x16x32_bf16 v[74:77], v[154:157], v[218:221], v[74:77]
	v_mfma_f32_16x16x32_bf16 v[126:129], v[134:137], v[192:195], v[126:129]
	v_mfma_f32_16x16x32_bf16 v[122:125], v[162:165], v[192:195], v[122:125]
	v_mfma_f32_16x16x32_bf16 v[110:113], v[134:137], v[200:203], v[110:113]
	v_mfma_f32_16x16x32_bf16 v[106:109], v[162:165], v[200:203], v[106:109]
	v_mfma_f32_16x16x32_bf16 v[94:97], v[134:137], v[214:217], v[94:97]
	v_mfma_f32_16x16x32_bf16 v[90:93], v[162:165], v[214:217], v[90:93]
	v_mfma_f32_16x16x32_bf16 v[78:81], v[134:137], v[222:225], v[78:81]
	v_mfma_f32_16x16x32_bf16 v[74:77], v[162:165], v[222:225], v[74:77]
	v_mfma_f32_16x16x32_bf16 v[118:121], v[166:169], v[188:191], v[118:121]
	v_mfma_f32_16x16x32_bf16 v[114:117], v[180:183], v[188:191], v[114:117]
	v_mfma_f32_16x16x32_bf16 v[102:105], v[166:169], v[196:199], v[102:105]
	v_mfma_f32_16x16x32_bf16 v[98:101], v[180:183], v[196:199], v[98:101]
	v_mfma_f32_16x16x32_bf16 v[86:89], v[166:169], v[210:213], v[86:89]
	v_mfma_f32_16x16x32_bf16 v[82:85], v[180:183], v[210:213], v[82:85]
	v_mfma_f32_16x16x32_bf16 v[70:73], v[166:169], v[218:221], v[70:73]
	v_mfma_f32_16x16x32_bf16 v[66:69], v[180:183], v[218:221], v[66:69]
	v_mfma_f32_16x16x32_bf16 v[118:121], v[170:173], v[192:195], v[118:121]
	v_mfma_f32_16x16x32_bf16 v[114:117], v[184:187], v[192:195], v[114:117]
	v_mfma_f32_16x16x32_bf16 v[102:105], v[170:173], v[200:203], v[102:105]
	v_mfma_f32_16x16x32_bf16 v[98:101], v[184:187], v[200:203], v[98:101]
	v_mfma_f32_16x16x32_bf16 v[86:89], v[170:173], v[214:217], v[86:89]
	v_mfma_f32_16x16x32_bf16 v[82:85], v[184:187], v[214:217], v[82:85]
	v_mfma_f32_16x16x32_bf16 v[70:73], v[170:173], v[222:225], v[70:73]
	v_mfma_f32_16x16x32_bf16 v[66:69], v[184:187], v[222:225], v[66:69]
	s_barrier
	s_add_i32 s46, s54, s15
	v_lshl_add_u64 v[226:227], v[226:227], 0, s[34:35]
	s_mov_b32 m0, s46
	ds_read_b128 v[188:191], v179 offset:49152
	ds_read_b128 v[192:195], v179 offset:50176
	ds_read_b128 v[196:199], v179 offset:51200
	ds_read_b128 v[200:203], v179 offset:52224
	ds_read_b128 v[210:213], v179 offset:53248
	ds_read_b128 v[214:217], v179 offset:54272
	ds_read_b128 v[218:221], v179 offset:55296
	ds_read_b128 v[222:225], v179 offset:56320
	global_load_lds_dwordx4 v[226:227], off
	s_add_i32 m0, s46, 0x2000
	s_add_u32 s22, s22, 0x80080
	v_lshl_add_u64 v[226:227], v[228:229], 0, s[34:35]
	s_addc_u32 s23, s23, 0
	s_add_i32 s46, s55, s15
	global_load_lds_dwordx4 v[226:227], off
	s_mov_b32 m0, s46
	s_nop 0
	global_load_lds_dwordx4 v142, s[22:23]
	s_add_i32 m0, s46, 0x2000
	s_nop 0
	global_load_lds_dwordx4 v138, s[22:23]
	v_lshl_add_u64 v[226:227], v[230:231], 0, s[34:35]
	s_mov_b32 m0, s49
	s_nop 0
	global_load_lds_dwordx4 v[226:227], off
	v_lshl_add_u64 v[226:227], v[232:233], 0, s[34:35]
	s_mov_b32 m0, s50
	s_nop 0
	global_load_lds_dwordx4 v[226:227], off
	s_waitcnt vmcnt(8)
	s_waitcnt lgkmcnt(0)
	s_barrier
	s_waitcnt lgkmcnt(0)
	v_mfma_f32_16x16x32_bf16 v[62:65], v[130:133], v[188:191], v[62:65]
	v_mfma_f32_16x16x32_bf16 v[58:61], v[154:157], v[188:191], v[58:61]
	v_mfma_f32_16x16x32_bf16 v[46:49], v[130:133], v[196:199], v[46:49]
	v_mfma_f32_16x16x32_bf16 v[42:45], v[154:157], v[196:199], v[42:45]
	v_mfma_f32_16x16x32_bf16 v[30:33], v[130:133], v[210:213], v[30:33]
	v_mfma_f32_16x16x32_bf16 v[26:29], v[154:157], v[210:213], v[26:29]
	v_mfma_f32_16x16x32_bf16 v[14:17], v[130:133], v[218:221], v[14:17]
	v_mfma_f32_16x16x32_bf16 v[10:13], v[154:157], v[218:221], v[10:13]
	v_mfma_f32_16x16x32_bf16 v[62:65], v[134:137], v[192:195], v[62:65]
	v_mfma_f32_16x16x32_bf16 v[58:61], v[162:165], v[192:195], v[58:61]
	v_mfma_f32_16x16x32_bf16 v[46:49], v[134:137], v[200:203], v[46:49]
	v_mfma_f32_16x16x32_bf16 v[42:45], v[162:165], v[200:203], v[42:45]
	v_mfma_f32_16x16x32_bf16 v[30:33], v[134:137], v[214:217], v[30:33]
	v_mfma_f32_16x16x32_bf16 v[26:29], v[162:165], v[214:217], v[26:29]
	v_mfma_f32_16x16x32_bf16 v[14:17], v[134:137], v[222:225], v[14:17]
	v_mfma_f32_16x16x32_bf16 v[10:13], v[162:165], v[222:225], v[10:13]
	v_mfma_f32_16x16x32_bf16 v[54:57], v[166:169], v[188:191], v[54:57]
	v_mfma_f32_16x16x32_bf16 v[50:53], v[180:183], v[188:191], v[50:53]
	v_mfma_f32_16x16x32_bf16 v[38:41], v[166:169], v[196:199], v[38:41]
	v_mfma_f32_16x16x32_bf16 v[34:37], v[180:183], v[196:199], v[34:37]
	v_mfma_f32_16x16x32_bf16 v[22:25], v[166:169], v[210:213], v[22:25]
	v_mfma_f32_16x16x32_bf16 v[18:21], v[180:183], v[210:213], v[18:21]
	v_mfma_f32_16x16x32_bf16 v[6:9], v[166:169], v[218:221], v[6:9]
	v_mfma_f32_16x16x32_bf16 v[2:5], v[180:183], v[218:221], v[2:5]
	v_mfma_f32_16x16x32_bf16 v[54:57], v[170:173], v[192:195], v[54:57]
	v_mfma_f32_16x16x32_bf16 v[50:53], v[184:187], v[192:195], v[50:53]
	v_mfma_f32_16x16x32_bf16 v[38:41], v[170:173], v[200:203], v[38:41]
	v_mfma_f32_16x16x32_bf16 v[34:37], v[184:187], v[200:203], v[34:37]
	v_mfma_f32_16x16x32_bf16 v[22:25], v[170:173], v[214:217], v[22:25]
	v_mfma_f32_16x16x32_bf16 v[18:21], v[184:187], v[214:217], v[18:21]
	v_mfma_f32_16x16x32_bf16 v[6:9], v[170:173], v[222:225], v[6:9]
	v_mfma_f32_16x16x32_bf16 v[2:5], v[184:187], v[222:225], v[2:5]
	s_barrier
	s_add_i32 s53, s53, 2
	s_add_u32 s6, s6, 0x100
	s_addc_u32 s7, s7, 0
	s_add_u32 s41, s41, 0x100
	s_addc_u32 s52, s52, 0
	s_cmp_gt_u32 s53, 29
	s_cbranch_scc0 .LBB0_604
	s_and_b64 vcc, exec, s[12:13]
	s_cbranch_vccz .LBB0_607
	s_barrier

.LBB0_728:
	s_add_u32 s42, s22, 0x100
	s_addc_u32 s43, s23, 0
	s_add_i32 s50, 0, 0x10000
	s_cmpk_eq_i32 s25, 0x54
	s_cselect_b32 s49, s21, s43
	s_cselect_b32 s48, s20, s42
	s_cselect_b32 s47, s45, s19
	s_cselect_b32 s46, s44, s18
	s_add_i32 s51, 0, 0x14000
	v_add_u32_e32 v54, s50, v176
	v_add_u32_e32 v179, s51, v176
	ds_read_b128 v[42:45], v54
	ds_read_b128 v[46:49], v54 offset:1024
	ds_read_b128 v[50:53], v54 offset:2048
	ds_read_b128 v[54:57], v54 offset:3072
	ds_read_b128 v[154:157], v179
	ds_read_b128 v[168:171], v179 offset:1024
	ds_read_b128 v[172:175], v179 offset:2048
	ds_read_b128 v[180:183], v179 offset:3072
	s_add_i32 m0, s33, 0xc000
	ds_read_b128 v[184:187], v178
	ds_read_b128 v[188:191], v178 offset:1024
	ds_read_b128 v[192:195], v178 offset:2048
	ds_read_b128 v[196:199], v178 offset:3072
	ds_read_b128 v[200:203], v178 offset:4096
	ds_read_b128 v[210:213], v178 offset:5120
	ds_read_b128 v[214:217], v178 offset:6144
	ds_read_b128 v[218:221], v178 offset:7168
	global_load_lds_dwordx4 v164, s[22:23]
	s_add_i32 m0, s33, 0xe000
	s_nop 0
	global_load_lds_dwordx4 v166, s[22:23]
	s_waitcnt vmcnt(8)
	s_waitcnt lgkmcnt(0)
	s_barrier
	s_waitcnt lgkmcnt(0)
	v_mfma_f32_16x16x32_bf16 v[142:145], v[42:45], v[184:187], v[142:145]
	v_mfma_f32_16x16x32_bf16 v[138:141], v[50:53], v[184:187], v[138:141]
	v_mfma_f32_16x16x32_bf16 v[126:129], v[42:45], v[192:195], v[126:129]
	v_mfma_f32_16x16x32_bf16 v[122:125], v[50:53], v[192:195], v[122:125]
	v_mfma_f32_16x16x32_bf16 v[110:113], v[42:45], v[200:203], v[110:113]
	v_mfma_f32_16x16x32_bf16 v[106:109], v[50:53], v[200:203], v[106:109]
	v_mfma_f32_16x16x32_bf16 v[94:97], v[42:45], v[214:217], v[94:97]
	v_mfma_f32_16x16x32_bf16 v[90:93], v[50:53], v[214:217], v[90:93]
	v_mfma_f32_16x16x32_bf16 v[142:145], v[46:49], v[188:191], v[142:145]
	v_mfma_f32_16x16x32_bf16 v[138:141], v[54:57], v[188:191], v[138:141]
	v_mfma_f32_16x16x32_bf16 v[126:129], v[46:49], v[196:199], v[126:129]
	v_mfma_f32_16x16x32_bf16 v[122:125], v[54:57], v[196:199], v[122:125]
	v_mfma_f32_16x16x32_bf16 v[110:113], v[46:49], v[210:213], v[110:113]
	v_mfma_f32_16x16x32_bf16 v[106:109], v[54:57], v[210:213], v[106:109]
	v_mfma_f32_16x16x32_bf16 v[94:97], v[46:49], v[218:221], v[94:97]
	v_mfma_f32_16x16x32_bf16 v[90:93], v[54:57], v[218:221], v[90:93]
	v_mfma_f32_16x16x32_bf16 v[134:137], v[154:157], v[184:187], v[134:137]
	v_mfma_f32_16x16x32_bf16 v[130:133], v[172:175], v[184:187], v[130:133]
	v_mfma_f32_16x16x32_bf16 v[118:121], v[154:157], v[192:195], v[118:121]
	v_mfma_f32_16x16x32_bf16 v[114:117], v[172:175], v[192:195], v[114:117]
	v_mfma_f32_16x16x32_bf16 v[102:105], v[154:157], v[200:203], v[102:105]
	v_mfma_f32_16x16x32_bf16 v[98:101], v[172:175], v[200:203], v[98:101]
	v_mfma_f32_16x16x32_bf16 v[86:89], v[154:157], v[214:217], v[86:89]
	v_mfma_f32_16x16x32_bf16 v[82:85], v[172:175], v[214:217], v[82:85]
	v_mfma_f32_16x16x32_bf16 v[134:137], v[168:171], v[188:191], v[134:137]
	v_mfma_f32_16x16x32_bf16 v[130:133], v[180:183], v[188:191], v[130:133]
	v_mfma_f32_16x16x32_bf16 v[118:121], v[168:171], v[196:199], v[118:121]
	v_mfma_f32_16x16x32_bf16 v[114:117], v[180:183], v[196:199], v[114:117]
	v_mfma_f32_16x16x32_bf16 v[102:105], v[168:171], v[210:213], v[102:105]
	v_mfma_f32_16x16x32_bf16 v[98:101], v[180:183], v[210:213], v[98:101]
	v_mfma_f32_16x16x32_bf16 v[86:89], v[168:171], v[218:221], v[86:89]
	v_mfma_f32_16x16x32_bf16 v[82:85], v[180:183], v[218:221], v[82:85]
	s_barrier
	s_add_i32 s22, s50, s16
	v_lshl_add_u64 v[222:223], s[46:47], 0, v[0:1]
	s_mov_b32 m0, s22
	ds_read_b128 v[184:187], v178 offset:16384
	ds_read_b128 v[188:191], v178 offset:17408
	ds_read_b128 v[192:195], v178 offset:18432
	ds_read_b128 v[196:199], v178 offset:19456
	ds_read_b128 v[200:203], v178 offset:20480
	ds_read_b128 v[210:213], v178 offset:21504
	ds_read_b128 v[214:217], v178 offset:22528
	ds_read_b128 v[218:221], v178 offset:23552
	global_load_lds_dwordx4 v[222:223], off
	s_add_i32 m0, s22, 0x2000
	s_add_u32 s22, s46, 0x160000
	v_lshl_add_u64 v[224:225], s[46:47], 0, v[158:159]
	s_addc_u32 s23, s47, 0
	s_add_i32 s50, s51, s16
	global_load_lds_dwordx4 v[224:225], off
	s_mov_b32 m0, s50
	v_lshl_add_u64 v[228:229], s[48:49], 0, v[160:161]
	global_load_lds_dwordx4 v0, s[22:23]
	s_add_i32 m0, s50, 0x2000
	s_nop 0
	global_load_lds_dwordx4 v158, s[22:23]
	v_lshl_add_u64 v[226:227], s[48:49], 0, v[162:163]
	s_mov_b32 m0, s33
	s_nop 0
	global_load_lds_dwordx4 v[226:227], off
	s_mov_b32 m0, s37
	s_nop 0
	global_load_lds_dwordx4 v[228:229], off
	s_waitcnt vmcnt(8)
	s_waitcnt lgkmcnt(0)
	s_barrier
	s_waitcnt lgkmcnt(0)
	v_mfma_f32_16x16x32_bf16 v[78:81], v[42:45], v[184:187], v[78:81]
	v_mfma_f32_16x16x32_bf16 v[74:77], v[50:53], v[184:187], v[74:77]
	v_mfma_f32_16x16x32_bf16 v[62:65], v[42:45], v[192:195], v[62:65]
	v_mfma_f32_16x16x32_bf16 v[58:61], v[50:53], v[192:195], v[58:61]
	v_mfma_f32_16x16x32_bf16 v[30:33], v[42:45], v[200:203], v[30:33]
	v_mfma_f32_16x16x32_bf16 v[26:29], v[50:53], v[200:203], v[26:29]
	v_mfma_f32_16x16x32_bf16 v[14:17], v[42:45], v[214:217], v[14:17]
	v_mfma_f32_16x16x32_bf16 v[10:13], v[50:53], v[214:217], v[10:13]
	v_mfma_f32_16x16x32_bf16 v[78:81], v[46:49], v[188:191], v[78:81]
	v_mfma_f32_16x16x32_bf16 v[74:77], v[54:57], v[188:191], v[74:77]
	v_mfma_f32_16x16x32_bf16 v[62:65], v[46:49], v[196:199], v[62:65]
	v_mfma_f32_16x16x32_bf16 v[58:61], v[54:57], v[196:199], v[58:61]
	v_mfma_f32_16x16x32_bf16 v[30:33], v[46:49], v[210:213], v[30:33]
	v_mfma_f32_16x16x32_bf16 v[26:29], v[54:57], v[210:213], v[26:29]
	v_mfma_f32_16x16x32_bf16 v[14:17], v[46:49], v[218:221], v[14:17]
	v_mfma_f32_16x16x32_bf16 v[10:13], v[54:57], v[218:221], v[10:13]
	v_mfma_f32_16x16x32_bf16 v[38:41], v[154:157], v[192:195], v[38:41]
	v_mfma_f32_16x16x32_bf16 v[34:37], v[172:175], v[192:195], v[34:37]
	v_mfma_f32_16x16x32_bf16 v[22:25], v[154:157], v[200:203], v[22:25]
	v_mfma_f32_16x16x32_bf16 v[18:21], v[172:175], v[200:203], v[18:21]
	v_mfma_f32_16x16x32_bf16 v[6:9], v[154:157], v[214:217], v[6:9]
	v_mfma_f32_16x16x32_bf16 v[2:5], v[172:175], v[214:217], v[2:5]
	v_mfma_f32_16x16x32_bf16 v[42:45], v[154:157], v[184:187], v[70:73]
	v_mfma_f32_16x16x32_bf16 v[46:49], v[172:175], v[184:187], v[66:69]
	v_mfma_f32_16x16x32_bf16 v[38:41], v[168:171], v[196:199], v[38:41]
	v_mfma_f32_16x16x32_bf16 v[34:37], v[180:183], v[196:199], v[34:37]
	v_mfma_f32_16x16x32_bf16 v[22:25], v[168:171], v[210:213], v[22:25]
	v_mfma_f32_16x16x32_bf16 v[18:21], v[180:183], v[210:213], v[18:21]
	v_mfma_f32_16x16x32_bf16 v[6:9], v[168:171], v[218:221], v[6:9]
	v_mfma_f32_16x16x32_bf16 v[2:5], v[180:183], v[218:221], v[2:5]
	v_mfma_f32_16x16x32_bf16 v[42:45], v[168:171], v[188:191], v[42:45]
	v_mfma_f32_16x16x32_bf16 v[46:49], v[180:183], v[188:191], v[46:49]
	s_barrier
	s_add_i32 s50, 0, 0x18000
	s_add_i32 s51, 0, 0x1c000
	v_add_u32_e32 v70, s50, v176
	v_add_u32_e32 v179, s51, v176
	ds_read_b128 v[50:53], v70
	ds_read_b128 v[54:57], v70 offset:1024
	ds_read_b128 v[66:69], v70 offset:2048
	ds_read_b128 v[70:73], v70 offset:3072
	ds_read_b128 v[154:157], v179
	ds_read_b128 v[168:171], v179 offset:1024
	ds_read_b128 v[172:175], v179 offset:2048
	ds_read_b128 v[180:183], v179 offset:3072
	s_add_u32 s22, s48, 0x160000
	s_addc_u32 s23, s49, 0
	s_mov_b32 m0, s52
	ds_read_b128 v[184:187], v178 offset:32768
	ds_read_b128 v[188:191], v178 offset:33792
	ds_read_b128 v[192:195], v178 offset:34816
	ds_read_b128 v[196:199], v178 offset:35840
	ds_read_b128 v[200:203], v178 offset:36864
	ds_read_b128 v[210:213], v178 offset:37888
	ds_read_b128 v[214:217], v178 offset:38912
	ds_read_b128 v[218:221], v178 offset:39936
	global_load_lds_dwordx4 v162, s[22:23]
	s_mov_b32 m0, s53
	s_nop 0
	global_load_lds_dwordx4 v160, s[22:23]
	s_waitcnt vmcnt(8)
	s_waitcnt lgkmcnt(0)
	s_barrier
	s_waitcnt lgkmcnt(0)
	v_mfma_f32_16x16x32_bf16 v[142:145], v[50:53], v[184:187], v[142:145]
	v_mfma_f32_16x16x32_bf16 v[138:141], v[66:69], v[184:187], v[138:141]
	v_mfma_f32_16x16x32_bf16 v[126:129], v[50:53], v[192:195], v[126:129]
	v_mfma_f32_16x16x32_bf16 v[122:125], v[66:69], v[192:195], v[122:125]
	v_mfma_f32_16x16x32_bf16 v[110:113], v[50:53], v[200:203], v[110:113]
	v_mfma_f32_16x16x32_bf16 v[106:109], v[66:69], v[200:203], v[106:109]
	v_mfma_f32_16x16x32_bf16 v[94:97], v[50:53], v[214:217], v[94:97]
	v_mfma_f32_16x16x32_bf16 v[90:93], v[66:69], v[214:217], v[90:93]
	v_mfma_f32_16x16x32_bf16 v[142:145], v[54:57], v[188:191], v[142:145]
	v_mfma_f32_16x16x32_bf16 v[138:141], v[70:73], v[188:191], v[138:141]
	v_mfma_f32_16x16x32_bf16 v[126:129], v[54:57], v[196:199], v[126:129]
	v_mfma_f32_16x16x32_bf16 v[122:125], v[70:73], v[196:199], v[122:125]
	v_mfma_f32_16x16x32_bf16 v[110:113], v[54:57], v[210:213], v[110:113]
	v_mfma_f32_16x16x32_bf16 v[106:109], v[70:73], v[210:213], v[106:109]
	v_mfma_f32_16x16x32_bf16 v[94:97], v[54:57], v[218:221], v[94:97]
	v_mfma_f32_16x16x32_bf16 v[90:93], v[70:73], v[218:221], v[90:93]
	v_mfma_f32_16x16x32_bf16 v[134:137], v[154:157], v[184:187], v[134:137]
	v_mfma_f32_16x16x32_bf16 v[130:133], v[172:175], v[184:187], v[130:133]
	v_mfma_f32_16x16x32_bf16 v[118:121], v[154:157], v[192:195], v[118:121]
	v_mfma_f32_16x16x32_bf16 v[114:117], v[172:175], v[192:195], v[114:117]
	v_mfma_f32_16x16x32_bf16 v[102:105], v[154:157], v[200:203], v[102:105]
	v_mfma_f32_16x16x32_bf16 v[98:101], v[172:175], v[200:203], v[98:101]
	v_mfma_f32_16x16x32_bf16 v[86:89], v[154:157], v[214:217], v[86:89]
	v_mfma_f32_16x16x32_bf16 v[82:85], v[172:175], v[214:217], v[82:85]
	v_mfma_f32_16x16x32_bf16 v[134:137], v[168:171], v[188:191], v[134:137]
	v_mfma_f32_16x16x32_bf16 v[130:133], v[180:183], v[188:191], v[130:133]
	v_mfma_f32_16x16x32_bf16 v[118:121], v[168:171], v[196:199], v[118:121]
	v_mfma_f32_16x16x32_bf16 v[114:117], v[180:183], v[196:199], v[114:117]
	v_mfma_f32_16x16x32_bf16 v[102:105], v[168:171], v[210:213], v[102:105]
	v_mfma_f32_16x16x32_bf16 v[98:101], v[180:183], v[210:213], v[98:101]
	v_mfma_f32_16x16x32_bf16 v[86:89], v[168:171], v[218:221], v[86:89]
	v_mfma_f32_16x16x32_bf16 v[82:85], v[180:183], v[218:221], v[82:85]
	s_barrier
	s_add_i32 s22, s50, s16
	v_lshl_add_u64 v[222:223], v[222:223], 0, s[34:35]
	s_mov_b32 m0, s22
	ds_read_b128 v[184:187], v178 offset:49152
	ds_read_b128 v[188:191], v178 offset:50176
	ds_read_b128 v[192:195], v178 offset:51200
	ds_read_b128 v[196:199], v178 offset:52224
	ds_read_b128 v[200:203], v178 offset:53248
	ds_read_b128 v[210:213], v178 offset:54272
	ds_read_b128 v[214:217], v178 offset:55296
	ds_read_b128 v[218:221], v178 offset:56320
	global_load_lds_dwordx4 v[222:223], off
	s_add_i32 m0, s22, 0x2000
	s_add_u32 s22, s46, 0x160080
	v_lshl_add_u64 v[222:223], v[224:225], 0, s[34:35]
	s_addc_u32 s23, s47, 0
	s_add_i32 s46, s51, s16
	global_load_lds_dwordx4 v[222:223], off
	s_mov_b32 m0, s46
	s_nop 0
	global_load_lds_dwordx4 v0, s[22:23]
	s_add_i32 m0, s46, 0x2000
	s_nop 0
	global_load_lds_dwordx4 v158, s[22:23]
	v_lshl_add_u64 v[222:223], v[226:227], 0, s[34:35]
	s_mov_b32 m0, s55
	s_nop 0
	global_load_lds_dwordx4 v[222:223], off
	v_lshl_add_u64 v[222:223], v[228:229], 0, s[34:35]
	s_mov_b32 m0, s56
	s_nop 0
	global_load_lds_dwordx4 v[222:223], off
	s_waitcnt vmcnt(8)
	s_waitcnt lgkmcnt(0)
	s_barrier
	s_waitcnt lgkmcnt(0)
	v_mfma_f32_16x16x32_bf16 v[78:81], v[50:53], v[184:187], v[78:81]
	v_mfma_f32_16x16x32_bf16 v[74:77], v[66:69], v[184:187], v[74:77]
	v_mfma_f32_16x16x32_bf16 v[62:65], v[50:53], v[192:195], v[62:65]
	v_mfma_f32_16x16x32_bf16 v[58:61], v[66:69], v[192:195], v[58:61]
	v_mfma_f32_16x16x32_bf16 v[30:33], v[50:53], v[200:203], v[30:33]
	v_mfma_f32_16x16x32_bf16 v[26:29], v[66:69], v[200:203], v[26:29]
	v_mfma_f32_16x16x32_bf16 v[14:17], v[50:53], v[214:217], v[14:17]
	v_mfma_f32_16x16x32_bf16 v[10:13], v[66:69], v[214:217], v[10:13]
	v_mfma_f32_16x16x32_bf16 v[78:81], v[54:57], v[188:191], v[78:81]
	v_mfma_f32_16x16x32_bf16 v[74:77], v[70:73], v[188:191], v[74:77]
	v_mfma_f32_16x16x32_bf16 v[62:65], v[54:57], v[196:199], v[62:65]
	v_mfma_f32_16x16x32_bf16 v[58:61], v[70:73], v[196:199], v[58:61]
	v_mfma_f32_16x16x32_bf16 v[30:33], v[54:57], v[210:213], v[30:33]
	v_mfma_f32_16x16x32_bf16 v[26:29], v[70:73], v[210:213], v[26:29]
	v_mfma_f32_16x16x32_bf16 v[14:17], v[54:57], v[218:221], v[14:17]
	v_mfma_f32_16x16x32_bf16 v[10:13], v[70:73], v[218:221], v[10:13]
	v_mfma_f32_16x16x32_bf16 v[42:45], v[154:157], v[184:187], v[42:45]
	v_mfma_f32_16x16x32_bf16 v[70:73], v[168:171], v[188:191], v[42:45]
	v_mfma_f32_16x16x32_bf16 v[42:45], v[172:175], v[184:187], v[46:49]
	v_mfma_f32_16x16x32_bf16 v[38:41], v[154:157], v[192:195], v[38:41]
	v_mfma_f32_16x16x32_bf16 v[34:37], v[172:175], v[192:195], v[34:37]
	v_mfma_f32_16x16x32_bf16 v[22:25], v[154:157], v[200:203], v[22:25]
	v_mfma_f32_16x16x32_bf16 v[18:21], v[172:175], v[200:203], v[18:21]
	v_mfma_f32_16x16x32_bf16 v[6:9], v[154:157], v[214:217], v[6:9]
	v_mfma_f32_16x16x32_bf16 v[2:5], v[172:175], v[214:217], v[2:5]
	v_mfma_f32_16x16x32_bf16 v[66:69], v[180:183], v[188:191], v[42:45]
	v_mfma_f32_16x16x32_bf16 v[38:41], v[168:171], v[196:199], v[38:41]
	v_mfma_f32_16x16x32_bf16 v[34:37], v[180:183], v[196:199], v[34:37]
	v_mfma_f32_16x16x32_bf16 v[22:25], v[168:171], v[210:213], v[22:25]
	v_mfma_f32_16x16x32_bf16 v[18:21], v[180:183], v[210:213], v[18:21]
	v_mfma_f32_16x16x32_bf16 v[6:9], v[168:171], v[218:221], v[6:9]
	v_mfma_f32_16x16x32_bf16 v[2:5], v[180:183], v[218:221], v[2:5]
	s_barrier
	s_add_i32 s25, s25, 2
	s_add_u32 s18, s18, 0x100
	s_addc_u32 s19, s19, 0
	s_cmpk_gt_u32 s25, 0x55
	s_mov_b64 s[22:23], s[42:43]
	s_cbranch_scc0 .LBB0_728
	s_and_b64 vcc, exec, s[12:13]
	s_cbranch_vccz .LBB0_731
	s_barrier
